# hgrn pass-1 block loop: a block's output-gate load issued at the top of the block instead of right before its use
# speedup vs baseline: 1.0109x; 1.0109x over previous
; __device__ __forceinline__ unsigned pk2(float lo, float hi) { unsigned r; asm("v_cvt_pk_bf16_f32 %0, %1, %2" : "=v"(r) : "v"(lo), "v"(hi)); return r; }
; __device__ __forceinline__ float bf2f(unsigned b) { return __uint_as_float(b << 16); }
; __device__ __forceinline__ float bflo(unsigned w) { return __uint_as_float(w << 16); }
; __device__ __forceinline__ float bfhi(unsigned w) { return __uint_as_float(w & 0xffff0000u); }
; __device__ __forceinline__ float sigm(float x) { return frcp(1.f + fexp(-x)); }
; __device__ __forceinline__ float silu(float x) { return x * sigm(x); }
; __device__ __forceinline__ void hgrn_item(const Params& p, int l, int item, int pass, LAS unsigned char* lds) {
;     ...
;     HG_LOAD(0);
;     for (int n = 0; n < 8; ++n) {
;         const size_t T0 = (size_t)b * SEQ + seg * 128 + n * 16;
;         float qv[4], fz[4]; unsigned vv[4];
; #pragma unroll
;         for (int j = 0; j < 4; ++j) { qv[j] = bf2f(qn[j]); fz[j] = bf2f(fn[j]); vv[j] = vn[j]; }
;         if (n < 7) HG_LOAD(n + 1);
;         u32x4 vw; vw.x = vv[0] | (vv[1] << 16); vw.y = vv[2] | (vv[3] << 16); vw.z = 0u; vw.w = 0u; const bf16x8 vfrag = as_bf8(vw);
;         float cs[4], kf[4]; float run = 0.f;
; #pragma unroll
;         for (int j = 0; j < 4; ++j) { const float sg = sigm(fz[j]); const float f = lbv + (1.f - lbv) * sg; run += __logf(fmaxf(f, 1e-30f)); cs[j] = run; kf[j] = (1.f - lbv) * sigm(-fz[j]); }
;         { const float t1 = __shfl(run, lane - 16), t2 = __shfl(run, lane - 32), t3 = __shfl(run, lane - 48);
;     ...
;             float ss = o[0] * o[0] + o[1] * o[1] + o[2] * o[2] + o[3] * o[3]; ss += __shfl_xor(ss, 16); ss += __shfl_xor(ss, 32);
;             if (fq == 0) ssq[wv * 16 + fr] = ss;
;             lds_barrier();
;             const float tot = ssq[fr] + ssq[16 + fr] + ssq[32 + fr] + ssq[48 + fr]; const float rstd = rsqrtf(tot * (1.f / 64.f) + EPS);
;             const size_t T = T0 + fr; const u32x2 gw = *(const u32x2*)(p.z + T * ZLD + 1536 + head * 64 + wv * 16 + fq * 4);
;             u32x2 w; w.x = pk2(o[0] * rstd * ng[0] * silu(bflo(gw.x)), o[1] * rstd * ng[1] * silu(bfhi(gw.x)));
;             w.y = pk2(o[2] * rstd * ng[2] * silu(bflo(gw.y)), o[3] * rstd * ng[3] * silu(bfhi(gw.y)));
;             *(u32x2*)(p.outs + ((size_t)1 * M + T) * 256 + head * 64 + wv * 16 + fq * 4) = w;
.LBB0_333:
	s_or_b64 exec, exec, s[18:19]
	s_waitcnt vmcnt(8)
	v_and_b32_e32 v79, 0xffff, v70
	s_waitcnt lgkmcnt(0)
	s_barrier
	v_add_u32_e32 v70, 0x1800, v45
	s_waitcnt lgkmcnt(0)
	ds_read2_b32 v[0:1], v70 offset0:192 offset1:208
	v_and_b32_e32 v61, 0xffff, v20
	v_and_b32_e32 v78, 0xffff, v22
	s_waitcnt vmcnt(4)
	v_and_b32_e32 v64, 0xffff, v74
	s_waitcnt vmcnt(3)
	v_and_b32_e32 v66, 0xffff, v75
	s_waitcnt lgkmcnt(0)
	v_add_f32_e32 v20, v0, v1
	ds_read2_b32 v[0:1], v70 offset0:224 offset1:240
	v_and_b32_e32 v63, 0xffff, v30
	v_and_b32_e32 v3, 0xffff, v28
	s_mov_b64 s[16:17], 0x2000
	v_and_b32_e32 v62, 0xffff, v71
	s_waitcnt lgkmcnt(0)
	v_add_f32_e32 v0, v20, v0
	v_add_f32_e32 v0, v0, v1
	v_fmamk_f32 v0, v0, 0x3c800000, v204
	v_cmp_gt_f32_e64 s[18:19], s93, v0
	v_mul_f32_e32 v1, 0x4b800000, v0
	v_and_b32_e32 v65, 0xffff, v72
	v_cndmask_b32_e64 v0, v0, v1, s[18:19]
	v_rsq_f32_e32 v0, v0
	v_and_b32_e32 v71, 0xffff, v73
	s_waitcnt vmcnt(2)
	v_and_b32_e32 v72, 0xffff, v76
	s_waitcnt vmcnt(1)
	v_and_b32_e32 v67, 0xffff, v77
	v_mul_f32_e32 v1, 0x45800000, v0
	v_cndmask_b32_e64 v22, v0, v1, s[18:19]
	v_mul_f32_e32 v75, v24, v22
	v_mul_f32_e32 v25, v25, v22
	s_add_u32 s70, s70, 0x16000
	s_addc_u32 s71, s71, 0
	s_cmp_eq_u32 s70, 0x9a000
	s_waitcnt vmcnt(0)
	v_mov_b32_e32 v0, v102
	v_mov_b32_e32 v1, v103
	v_lshlrev_b32_e32 v74, 16, v0
	v_and_b32_e32 v24, 0xffff0000, v0
	v_mul_f32_e32 v20, 0xbfb8aa3b, v74
	v_mul_f32_e32 v0, 0xbfb8aa3b, v24
	v_exp_f32_e32 v20, v20
	v_exp_f32_e32 v0, v0
	v_add_f32_e32 v20, 1.0, v20
	v_add_f32_e32 v0, 1.0, v0
	v_rcp_f32_e32 v30, v20
	v_rcp_f32_e32 v20, v0
	v_pk_mul_f32 v[74:75], v[30:31], v[74:75]
	v_pk_mul_f32 v[24:25], v[20:21], v[24:25]
	v_mul_f32_e32 v28, v74, v75
	v_mul_f32_e32 v0, v24, v25
	v_lshlrev_b32_e32 v24, 16, v1
	v_mul_f32_e32 v20, 0xbfb8aa3b, v24
	v_exp_f32_e32 v20, v20
	v_cvt_pk_bf16_f32 v0, v28, v0
	v_mul_f32_e32 v25, v26, v22
	v_add_f32_e32 v20, 1.0, v20
	v_rcp_f32_e32 v28, v20
	s_nop 0
	v_pk_mul_f32 v[24:25], v[28:29], v[24:25]
	s_nop 0
	v_mul_f32_e32 v20, v24, v25
	v_and_b32_e32 v24, 0xffff0000, v1
	v_mul_f32_e32 v1, 0xbfb8aa3b, v24
	v_exp_f32_e32 v1, v1
	v_mul_f32_e32 v25, v27, v22
	v_add_f32_e32 v1, 1.0, v1
	v_rcp_f32_e32 v22, v1
	s_nop 0
	v_pk_mul_f32 v[24:25], v[22:23], v[24:25]
	s_nop 0
	v_mul_f32_e32 v1, v24, v25
	v_cvt_pk_bf16_f32 v1, v20, v1
	global_store_dwordx2 v[38:39], v[0:1], off
	v_lshl_add_u64 v[38:39], v[38:39], 0, s[16:17]
	s_cbranch_scc1 .LBB0_338
.LBB0_334:
	v_lshl_add_u64 v[0:1], v[42:43], 0, s[70:71]
	v_add_co_u32_e64 v24, s[18:19], s38, v0
	s_waitcnt vmcnt(10)
	v_lshlrev_b32_e32 v26, 16, v78
	v_addc_co_u32_e64 v25, s[18:19], 0, v1, s[18:19]
	global_load_ushort v20, v[24:25], off offset:1536
	global_load_ushort v22, v[24:25], off offset:2048
	global_load_ushort v28, v[24:25], off offset:2560
	v_add_co_u32_e64 v24, s[18:19], s23, v0
	s_waitcnt vmcnt(7)
	v_lshlrev_b32_e32 v78, 16, v71
	v_addc_co_u32_e64 v25, s[18:19], 0, v1, s[18:19]
	global_load_ushort v30, v[24:25], off offset:3072
	global_load_ushort v70, v[24:25], off offset:3584
	v_add_co_u32_e64 v24, s[18:19], s83, v0
	v_lshlrev_b32_e32 v27, 16, v79
	s_nop 0
	v_addc_co_u32_e64 v25, s[18:19], 0, v1, s[18:19]
	global_load_ushort v71, v[24:25], off
	v_add_co_u32_e64 v24, s[18:19], s33, v0
	s_waitcnt vmcnt(7)
	v_lshlrev_b32_e32 v79, 16, v72
	v_addc_co_u32_e64 v25, s[18:19], 0, v1, s[18:19]
	v_add_co_u32_e64 v0, s[18:19], s22, v0
	global_load_ushort v72, v[24:25], off offset:512
	global_load_ushort v73, v[24:25], off offset:1024
	global_load_ushort v74, v[24:25], off offset:1536
	v_addc_co_u32_e64 v1, s[18:19], 0, v1, s[18:19]
	global_load_ushort v75, v[0:1], off offset:2048
	global_load_ushort v76, v[0:1], off offset:2560
	global_load_ushort v77, v[0:1], off offset:3072
	v_lshl_add_u64 v[104:105], v[40:41], 0, s[70:71]
	global_load_dwordx2 v[102:103], v[104:105], off
	v_mul_f32_e32 v0, 0xbfb8aa3b, v26
	v_exp_f32_e32 v0, v0
	s_waitcnt lgkmcnt(0)
	s_barrier
	v_add_f32_e32 v0, 1.0, v0
	v_rcp_f32_e32 v0, v0
	s_nop 0
	v_fma_f32 v0, v56, v0, v47
	v_max_f32_e32 v0, 0xda24260, v0
	v_cmp_gt_f32_e64 s[18:19], s93, v0
	s_nop 1
	v_cndmask_b32_e64 v1, 0, 32, s[18:19]
	v_ldexp_f32 v0, v0, v1
	v_log_f32_e32 v0, v0
	s_nop 0
	v_mul_f32_e32 v1, 0x3f317217, v0
	v_fma_f32 v1, v0, s85, -v1
	v_fmac_f32_e32 v1, 0x3377d1cf, v0
	v_fmac_f32_e32 v1, 0x3f317217, v0
	v_cmp_lt_f32_e64 s[20:21], |v0|, s78
	s_nop 1
	v_cndmask_b32_e64 v0, v0, v1, s[20:21]
	v_cndmask_b32_e64 v1, 0, v211, s[18:19]
	v_sub_f32_e32 v0, v0, v1
	v_mul_f32_e32 v1, 0x3fb8aa3b, v26
	v_exp_f32_e32 v1, v1
	v_mul_f32_e32 v26, 0xbfb8aa3b, v78
	v_exp_f32_e32 v26, v26
	v_add_f32_e32 v0, 0, v0
	v_add_f32_e32 v1, 1.0, v1
	v_rcp_f32_e32 v1, v1
	v_add_f32_e32 v26, 1.0, v26
	v_rcp_f32_e32 v26, v26
	v_mul_f32_e32 v24, v56, v1
	v_mul_f32_e32 v1, 0xbfb8aa3b, v27
	v_exp_f32_e32 v1, v1
	v_fma_f32 v26, v56, v26, v47
	v_max_f32_e32 v26, 0xda24260, v26
	v_add_f32_e32 v1, 1.0, v1
	v_rcp_f32_e32 v1, v1
	s_nop 0
	v_fma_f32 v1, v56, v1, v47
	v_max_f32_e32 v1, 0xda24260, v1
	v_cmp_gt_f32_e64 s[18:19], s93, v1
	s_nop 1
	v_cndmask_b32_e64 v25, 0, 32, s[18:19]
	v_ldexp_f32 v1, v1, v25
	v_log_f32_e32 v1, v1
	s_nop 0
	v_mul_f32_e32 v25, 0x3f317217, v1
	v_fma_f32 v25, v1, s85, -v25
	v_fmac_f32_e32 v25, 0x3377d1cf, v1
	v_fmac_f32_e32 v25, 0x3f317217, v1
	v_cmp_lt_f32_e64 s[20:21], |v1|, s78
	s_nop 1
	v_cndmask_b32_e64 v1, v1, v25, s[20:21]
	v_cndmask_b32_e64 v25, 0, v211, s[18:19]
	v_cmp_gt_f32_e64 s[18:19], s93, v26
	v_sub_f32_e32 v1, v1, v25
	v_mul_f32_e32 v25, 0x3fb8aa3b, v27
	v_cndmask_b32_e64 v27, 0, 32, s[18:19]
	v_ldexp_f32 v26, v26, v27
	v_log_f32_e32 v26, v26
	v_add_f32_e32 v1, v1, v0
	v_exp_f32_e32 v25, v25
	v_mul_f32_e32 v27, 0x3f317217, v26
	v_fma_f32 v27, v26, s85, -v27
	v_fmac_f32_e32 v27, 0x3377d1cf, v26
	v_fmac_f32_e32 v27, 0x3f317217, v26
	v_cmp_lt_f32_e64 s[20:21], |v26|, s78
	v_add_f32_e32 v25, 1.0, v25
	v_rcp_f32_e32 v25, v25
	v_cndmask_b32_e64 v26, v26, v27, s[20:21]
	v_cndmask_b32_e64 v27, 0, v211, s[18:19]
	v_sub_f32_e32 v26, v26, v27
	v_mul_f32_e32 v27, 0xbfb8aa3b, v79
	v_exp_f32_e32 v27, v27
	v_add_f32_e32 v82, v26, v1
	v_mul_f32_e32 v26, 0x3fb8aa3b, v78
	v_exp_f32_e32 v26, v26
	v_add_f32_e32 v27, 1.0, v27
	v_rcp_f32_e32 v27, v27
	v_mul_f32_e32 v25, v56, v25
	v_add_f32_e32 v26, 1.0, v26
	v_rcp_f32_e32 v26, v26
	v_fma_f32 v27, v56, v27, v47
	v_max_f32_e32 v27, 0xda24260, v27
	v_cmp_gt_f32_e64 s[18:19], s93, v27
	v_mul_f32_e32 v26, v56, v26
	s_nop 0
	v_cndmask_b32_e64 v78, 0, 32, s[18:19]
	v_ldexp_f32 v27, v27, v78
	v_log_f32_e32 v27, v27
	s_nop 0
	v_mul_f32_e32 v78, 0x3f317217, v27
	v_fma_f32 v78, v27, s85, -v78
	v_fmac_f32_e32 v78, 0x3377d1cf, v27
	v_fmac_f32_e32 v78, 0x3f317217, v27
	v_cmp_lt_f32_e64 s[20:21], |v27|, s78
	s_nop 1
	v_cndmask_b32_e64 v27, v27, v78, s[20:21]
	v_cndmask_b32_e64 v78, 0, v211, s[18:19]
	v_sub_f32_e32 v27, v27, v78
	v_add_f32_e32 v78, v27, v82
	v_mul_f32_e32 v27, 0x3fb8aa3b, v79
	ds_bpermute_b32 v79, v54, v78
	ds_bpermute_b32 v80, v55, v78
	ds_bpermute_b32 v81, v58, v78
	v_exp_f32_e32 v27, v27
	s_waitcnt lgkmcnt(2)
; #define LAS __attribute__((address_space(3)))
; __device__ __forceinline__ void hgrn_item(const Params& p, int l, int item, int pass, LAS unsigned char* lds) {
;     ...
;         { const float t1 = __shfl(run, lane - 16), t2 = __shfl(run, lane - 32), t3 = __shfl(run, lane - 48);
;           const float pre = (fq >= 1 ? t1 : 0.f) + (fq >= 2 ? t2 : 0.f) + (fq >= 3 ? t3 : 0.f);
; #pragma unroll
;           for (int j = 0; j < 4; ++j) cs[j] += pre; }
;         const float blast = __shfl(cs[3], 48 + fr);
;         lds_barrier();
;         { u32x2 w; w.x = pk2(kf[0] * fexp(blast - cs[0]), kf[1] * fexp(blast - cs[1])); w.y = pk2(kf[2] * fexp(blast - cs[2]), kf[3] * fexp(blast - cs[3]));
;           *(LAS u32x2*)(KHt + (wv * 16 + fr) * 16 + fq * 4) = w;
;           if (fq == 0) decs[wv * 16 + fr] = fexp(blast);
;           if (pass == 1) {
; #pragma unroll
;               for (int j = 0; j < 4; ++j) { const int s = fq * 4 + j; Qs[s * 72 + wv * 16 + fr] = f2bf(silu(qv[j]) * fexp(cs[j])); Ks[s * 72 + wv * 16 + fr] = f2bf(kf[j] * fexp(fminf(-cs[j], 80.f))); } } }
;         segb += blast;
;         lds_barrier();
;         f32x4 o = ZERO4;
;         if (pass == 1) {
;             const bf16x8 ka0 = *(const LAS bf16x8*)(Ks + fr * 72 + fq * 8), ka1 = *(const LAS bf16x8*)(Ks + fr * 72 + 32 + fq * 8);
;             const bf16x8 qb0 = *(const LAS bf16x8*)(Qs + fr * 72 + fq * 8), qb1 = *(const LAS bf16x8*)(Qs + fr * 72 + 32 + fq * 8);
;             f32x4 sc = mfma16(ka0, qb0, ZERO4); sc = mfma16(ka1, qb1, sc);
; #pragma unroll
;             for (int j = 0; j < 4; ++j) sc[j] = (fq * 4 + j <= fr) ? sc[j] : 0.f;
;             u32x4 pw; pw.x = pk2(sc[0], sc[1]); pw.y = pk2(sc[2], sc[3]); pw.z = 0u; pw.w = 0u;
;             o = mfma16(vfrag, as_bf8(pw), o);
; #pragma unroll
;             for (int kk = 0; kk < 2; ++kk) {
;                 u32x4 sw; sw.x = pk2(S[2 * kk][0], S[2 * kk][1]); sw.y = pk2(S[2 * kk][2], S[2 * kk][3]); sw.z = pk2(S[2 * kk + 1][0], S[2 * kk + 1][1]); sw.w = pk2(S[2 * kk + 1][2], S[2 * kk + 1][3]);
;                 const u32x2 q0 = *(const LAS u32x2*)(Qs + fr * 72 + (2 * kk) * 16 + fq * 4), q1 = *(const LAS u32x2*)(Qs + fr * 72 + (2 * kk + 1) * 16 + fq * 4);
;                 u32x4 qw; qw.x = q0.x; qw.y = q0.y; qw.z = q1.x; qw.w = q1.y;
;                 o = mfma16(as_bf8(sw), as_bf8(qw), o);
;             }
;         }
; #pragma unroll
	v_cndmask_b32_e64 v79, v79, 0, vcc
	s_waitcnt lgkmcnt(1)
	v_cndmask_b32_e64 v80, 0, v80, s[12:13]
	v_add_f32_e32 v79, v79, v80
	s_waitcnt lgkmcnt(0)
	v_cndmask_b32_e64 v80, 0, v81, s[14:15]
	v_add_f32_e32 v83, v79, v80
	v_add_f32_e32 v78, v78, v83
	v_add_f32_e32 v81, v0, v83
	ds_bpermute_b32 v0, v57, v78
	v_add_f32_e32 v80, v1, v83
	v_add_f32_e32 v79, v82, v83
	v_add_f32_e32 v27, 1.0, v27
	v_rcp_f32_e32 v27, v27
	s_waitcnt lgkmcnt(0)
	v_sub_f32_e32 v1, v0, v81
	v_sub_f32_e32 v82, v0, v80
	v_mul_f32_e32 v1, 0x3fb8aa3b, v1
	v_mul_f32_e32 v82, 0x3fb8aa3b, v82
	v_exp_f32_e32 v1, v1
	v_exp_f32_e32 v82, v82
	v_sub_f32_e32 v83, v0, v78
	v_mul_f32_e32 v83, 0x3fb8aa3b, v83
	v_mul_f32_e32 v1, v24, v1
	v_mul_f32_e32 v82, v25, v82
	v_cvt_pk_bf16_f32 v82, v1, v82
	v_sub_f32_e32 v1, v0, v79
	v_mul_f32_e32 v1, 0x3fb8aa3b, v1
	v_exp_f32_e32 v83, v83
	v_exp_f32_e32 v1, v1
	v_mul_f32_e32 v27, v56, v27
	v_mul_f32_e32 v83, v27, v83
	v_mul_f32_e32 v1, v26, v1
	v_cvt_pk_bf16_f32 v83, v1, v83
	ds_write_b64 v59, v[82:83] offset:4608
	s_and_saveexec_b64 s[18:19], vcc
	s_cbranch_execz .LBB0_336
	v_mul_f32_e32 v0, 0x3fb8aa3b, v0
	v_exp_f32_e32 v0, v0
	v_add_u32_e32 v1, v53, v60
	ds_write_b32 v1, v0 offset:6656
.LBB0_336:
	s_or_b64 exec, exec, s[18:19]
	v_lshlrev_b32_e32 v61, 16, v61
	v_lshl_or_b32 v0, v62, 16, v3
	v_mul_f32_e32 v62, 0xbfb8aa3b, v61
	v_exp_f32_e32 v62, v62
	v_lshlrev_b32_e32 v63, 16, v63
	v_lshlrev_b32_e32 v65, 16, v65
	v_lshlrev_b32_e32 v66, 16, v66
	v_add_f32_e32 v62, 1.0, v62
	v_rcp_f32_e32 v62, v62
	s_waitcnt vmcnt(13)
	v_lshl_or_b32 v1, v67, 16, v64
	v_mov_b32_e32 v3, v2
	v_mul_f32_e32 v61, v62, v61
	v_mul_f32_e32 v62, 0x3fb8aa3b, v81
	v_exp_f32_e32 v62, v62
	s_nop 0
	v_mul_f32_e32 v61, v61, v62
	v_cvt_pk_bf16_f32 v61, v61, v2
	ds_write_b16 v52, v61
	v_max_f32_e64 v61, -v81, -v81
	v_min_f32_e32 v61, 0x42a00000, v61
	v_mul_f32_e32 v61, 0x3fb8aa3b, v61
	v_exp_f32_e32 v61, v61
	s_nop 0
	v_mul_f32_e32 v24, v24, v61
	v_cvt_pk_bf16_f32 v24, v24, v2
	ds_write_b16 v52, v24 offset:2304
	v_mul_f32_e32 v24, 0xbfb8aa3b, v63
	v_exp_f32_e32 v24, v24
	v_mul_f32_e32 v61, 0x3fb8aa3b, v80
	v_exp_f32_e32 v61, v61
	v_add_f32_e32 v24, 1.0, v24
	v_rcp_f32_e32 v24, v24
	s_nop 0
	v_mul_f32_e32 v24, v24, v63
	v_mul_f32_e32 v24, v24, v61
	v_cvt_pk_bf16_f32 v24, v24, v2
	ds_write_b16 v52, v24 offset:144
	v_max_f32_e64 v24, -v80, -v80
	v_min_f32_e32 v24, 0x42a00000, v24
	v_mul_f32_e32 v24, 0x3fb8aa3b, v24
	v_exp_f32_e32 v24, v24
	v_add_u32_e32 v61, v69, v68
	v_mul_f32_e32 v24, v25, v24
	v_cvt_pk_bf16_f32 v24, v24, v2
	ds_write_b16 v52, v24 offset:2448
	v_mul_f32_e32 v24, 0xbfb8aa3b, v65
	v_exp_f32_e32 v24, v24
	v_mul_f32_e32 v25, 0x3fb8aa3b, v79
	v_exp_f32_e32 v25, v25
	v_add_f32_e32 v24, 1.0, v24
	v_rcp_f32_e32 v24, v24
	s_nop 0
	v_mul_f32_e32 v24, v24, v65
	v_mul_f32_e32 v24, v24, v25
	v_cvt_pk_bf16_f32 v24, v24, v2
	ds_write_b16 v52, v24 offset:288
	v_max_f32_e64 v24, -v79, -v79
	v_min_f32_e32 v24, 0x42a00000, v24
	v_mul_f32_e32 v24, 0x3fb8aa3b, v24
	v_exp_f32_e32 v24, v24
	v_mul_f32_e32 v25, 0x3fb8aa3b, v78
	v_exp_f32_e32 v25, v25
	v_mul_f32_e32 v24, v26, v24
	v_cvt_pk_bf16_f32 v24, v24, v2
	ds_write_b16 v52, v24 offset:2592
	v_mul_f32_e32 v24, 0xbfb8aa3b, v66
	v_exp_f32_e32 v24, v24
	s_nop 0
	v_add_f32_e32 v24, 1.0, v24
	v_rcp_f32_e32 v24, v24
	s_nop 0
	v_mul_f32_e32 v24, v24, v66
	v_mul_f32_e32 v24, v24, v25
	v_cvt_pk_bf16_f32 v24, v24, v2
	ds_write_b16 v52, v24 offset:432
	v_max_f32_e64 v24, -v78, -v78
	v_min_f32_e32 v24, 0x42a00000, v24
	v_mul_f32_e32 v24, 0x3fb8aa3b, v24
	v_exp_f32_e32 v24, v24
	s_nop 0
	v_mul_f32_e32 v24, v27, v24
	v_cvt_pk_bf16_f32 v24, v24, v2
	ds_write_b16 v52, v24 offset:2736
	s_waitcnt lgkmcnt(0)
	s_barrier
	ds_read_b128 v[24:27], v50 offset:2304
	ds_read_b128 v[62:65], v50 offset:2368
	ds_read_b128 v[78:81], v50
	ds_read_b128 v[82:85], v50 offset:64
	s_waitcnt lgkmcnt(1)
	v_mfma_f32_16x16x32_bf16 v[24:27], v[24:27], v[78:81], 0
	ds_read2_b64 v[78:81], v48 offset1:4
	s_waitcnt lgkmcnt(1)
	v_mfma_f32_16x16x32_bf16 v[24:27], v[62:65], v[82:85], v[24:27]
	v_cvt_pk_bf16_f32 v62, v12, v13
	v_cvt_pk_bf16_f32 v63, v14, v15
	v_cvt_pk_bf16_f32 v64, v16, v17
	v_cvt_pk_bf16_f32 v65, v18, v19
	ds_read_b128 v[82:85], v61 offset:6656
	s_nop 6
	v_cndmask_b32_e64 v24, v24, 0, s[4:5]
	v_cndmask_b32_e64 v25, 0, v25, s[6:7]
	v_cndmask_b32_e64 v26, v26, 0, s[8:9]
	v_cndmask_b32_e64 v27, v27, 0, s[10:11]
	v_cvt_pk_bf16_f32 v24, v24, v25
	v_cvt_pk_bf16_f32 v25, v26, v27
	v_mov_b32_e32 v26, v2
	v_mov_b32_e32 v27, v2
	s_waitcnt lgkmcnt(0)
	v_pk_mul_f32 v[12:13], v[12:13], v[82:83]
	v_pk_mul_f32 v[14:15], v[14:15], v[84:85]
	v_mfma_f32_16x16x32_bf16 v[24:27], v[0:3], v[24:27], 0
	v_mfma_f32_16x16x32_bf16 v[24:27], v[62:65], v[78:81], v[24:27]
	ds_read2_b64 v[78:81], v48 offset0:8 offset1:12
	v_cvt_pk_bf16_f32 v62, v4, v5
	v_cvt_pk_bf16_f32 v63, v6, v7
	v_cvt_pk_bf16_f32 v64, v8, v9
	v_cvt_pk_bf16_f32 v65, v10, v11
	s_waitcnt lgkmcnt(0)
	v_mfma_f32_16x16x32_bf16 v[24:27], v[62:65], v[78:81], v[24:27]
	ds_read2st64_b64 v[62:65], v35 offset0:9 offset1:10
	v_mov_b32_e32 v80, v2
	v_mov_b32_e32 v81, v2
	s_waitcnt lgkmcnt(0)
	v_mov_b32_e32 v78, v62
	v_mov_b32_e32 v79, v63
	v_mov_b32_e32 v62, v64
	v_mov_b32_e32 v63, v65
	v_mfma_f32_16x16x32_bf16 v[12:15], v[78:81], v[0:3], v[12:15]
	ds_read_b128 v[78:81], v61 offset:6720
	v_mov_b32_e32 v64, v2
	v_mov_b32_e32 v65, v2
	s_waitcnt lgkmcnt(0)
	v_pk_mul_f32 v[16:17], v[16:17], v[78:79]
	v_pk_mul_f32 v[18:19], v[18:19], v[80:81]
	s_nop 1
	v_mfma_f32_16x16x32_bf16 v[16:19], v[62:65], v[0:3], v[16:19]
	ds_read_b64 v[62:63], v35 offset:5632
	ds_read_b128 v[78:81], v61 offset:6784
	s_waitcnt lgkmcnt(0)
	v_pk_mul_f32 v[4:5], v[4:5], v[78:79]
	v_pk_mul_f32 v[6:7], v[6:7], v[80:81]
	s_nop 1
	v_mfma_f32_16x16x32_bf16 v[4:7], v[62:65], v[0:3], v[4:7]
	ds_read_b64 v[62:63], v44 offset:4608
	ds_read_b128 v[78:81], v61 offset:6848
	s_waitcnt lgkmcnt(0)
	v_pk_mul_f32 v[8:9], v[8:9], v[78:79]
	v_pk_mul_f32 v[10:11], v[10:11], v[80:81]
	s_nop 1
	v_mfma_f32_16x16x32_bf16 v[8:11], v[62:65], v[0:3], v[8:11]
	v_mul_f32_e32 v0, v25, v25
	v_fmac_f32_e32 v0, v24, v24
	v_fmac_f32_e32 v0, v26, v26
	v_fmac_f32_e32 v0, v27, v27
	ds_bpermute_b32 v1, v49, v0
	s_waitcnt lgkmcnt(0)
	v_add_f32_e32 v0, v0, v1
	ds_bpermute_b32 v1, v51, v0
	s_and_saveexec_b64 s[18:19], vcc
	s_cbranch_execz .LBB0_333
	s_waitcnt lgkmcnt(0)
	v_add_f32_e32 v0, v0, v1
	v_add_u32_e32 v1, v53, v60
	ds_write_b32 v1, v0 offset:6912
	s_branch .LBB0_333
